# layer-0 PEER table rows converted in the idle tails of the RGin and RGout GEMM phases (hand-written), removed from the layer-0 scores phase
# speedup vs baseline: 1.0794x; 1.0017x over previous
; __device__ __forceinline__ void peer_convert_rows(KP P, const Ctx& c, int g_lo, int g_hi, int rank, int nranks) {
;     ...
;     { const int gf = g_lo + (rank * 8 + c.wave) * 2; if (gf < g_hi) CV_LOAD(gf); }
;     for (int g0 = g_lo + (rank * 8 + c.wave) * 2; g0 < g_hi; g0 += nranks * 16) {
.LBB0_425:
	v_readlane_b32 s60, v244, 4
	s_cmpk_lg_i32 s60, 0x100
	s_cbranch_scc1 .Lcv0_A_done
	s_cmp_lt_u32 s2, 64
	s_cbranch_scc1 .Lcv0_A_done
	v_readfirstlane_b32 s63, v0
	s_lshr_b32 s89, s63, 6
	s_sub_i32 s62, s2, 64
	s_lshl_b32 s62, s62, 3
	s_add_i32 s89, s89, s62
.Lcv0_A_loop:
	s_cmp_ge_u32 s89, 0x2aab
	s_cbranch_scc1 .Lcv0_A_done
	s_lshl_b32 s61, s89, 1
	s_load_dwordx4 s[64:67], s[94:95], 0x50
	s_load_dwordx2 s[68:69], s[94:95], 0x130
	v_and_b32_e32 v102, 63, v0
	v_lshlrev_b32_e32 v103, 6, v102
	v_add_u32_e32 v104, 0x1000, v103
	v_lshrrev_b32_e32 v105, 3, v102
	v_and_b32_e32 v106, 7, v102
	v_lshlrev_b32_e32 v105, 21, v105
	v_lshl_or_b32 v105, v106, 4, v105
	v_add_u32_e32 v106, 0x1000000, v105
	v_mov_b32_e32 v204, 1.0
	v_mov_b32_e32 v206, 0
	s_add_i32 s70, s61, 1
	s_cmp_lt_u32 s70, 0xaaab
	s_cselect_b32 s88, 1, 0
	s_waitcnt lgkmcnt(0)
	s_lshr_b32 s71, s61, 14
	s_and_b32 s72, s61, 0x3fff
	s_lshr_b32 s73, s71, 1
	s_and_b32 s74, s71, 1
	s_cmp_eq_u32 s74, 0
	s_cselect_b32 s76, s64, s66
	s_cselect_b32 s77, s65, s67
	s_lshl_b32 s75, s73, 14
	s_add_i32 s75, s75, s72
	s_lshl_b32 s75, s75, 13
	s_add_u32 s76, s76, s75
	s_addc_u32 s77, s77, 0
	global_load_dwordx4 v[38:41], v103, s[76:77]
	global_load_dwordx4 v[42:45], v103, s[76:77] offset:16
	global_load_dwordx4 v[46:49], v103, s[76:77] offset:32
	global_load_dwordx4 v[50:53], v103, s[76:77] offset:48
	global_load_dwordx4 v[54:57], v104, s[76:77]
	global_load_dwordx4 v[58:61], v104, s[76:77] offset:16
	global_load_dwordx4 v[62:65], v104, s[76:77] offset:32
	global_load_dwordx4 v[66:69], v104, s[76:77] offset:48
	s_cmp_eq_u32 s88, 0
	s_cbranch_scc1 .Lrw_cv_l1_A
	s_lshr_b32 s71, s70, 14
	s_and_b32 s72, s70, 0x3fff
	s_lshr_b32 s73, s71, 1
	s_and_b32 s74, s71, 1
	s_cmp_eq_u32 s74, 0
	s_cselect_b32 s78, s64, s66
	s_cselect_b32 s79, s65, s67
	s_lshl_b32 s75, s73, 14
	s_add_i32 s75, s75, s72
	s_lshl_b32 s75, s75, 13
	s_add_u32 s78, s78, s75
	s_addc_u32 s79, s79, 0
	global_load_dwordx4 v[70:73], v103, s[78:79]
	global_load_dwordx4 v[74:77], v103, s[78:79] offset:16
	global_load_dwordx4 v[78:81], v103, s[78:79] offset:32
	global_load_dwordx4 v[82:85], v103, s[78:79] offset:48
	global_load_dwordx4 v[86:89], v104, s[78:79]
	global_load_dwordx4 v[90:93], v104, s[78:79] offset:16
	global_load_dwordx4 v[94:97], v104, s[78:79] offset:32
	global_load_dwordx4 v[98:101], v104, s[78:79] offset:48

; __device__ __forceinline__ void peer_convert_rows(KP P, const Ctx& c, int g_lo, int g_hi, int rank, int nranks) {
;     ...
;     for (int g0 = g_lo + (rank * 8 + c.wave) * 2; g0 < g_hi; g0 += nranks * 16) {
.Lcv0_A_next:
	s_add_i32 s89, s89, 0x600
	s_branch .Lcv0_A_loop

; __device__ __forceinline__ void peer_convert_rows(KP P, const Ctx& c, int g_lo, int g_hi, int rank, int nranks) {
;     ...
;     { const int gf = g_lo + (rank * 8 + c.wave) * 2; if (gf < g_hi) CV_LOAD(gf); }
;     for (int g0 = g_lo + (rank * 8 + c.wave) * 2; g0 < g_hi; g0 += nranks * 16) {
.LBB0_904:
	v_readlane_b32 s60, v244, 4
	s_cmpk_lg_i32 s60, 0x100
	s_cbranch_scc1 .Lcv0_B_done
	s_cmp_lt_u32 s2, 32
	s_cbranch_scc1 .Lcv0_B_done
	v_readfirstlane_b32 s63, v0
	s_lshr_b32 s89, s63, 6
	s_sub_i32 s62, s2, 32
	s_lshl_b32 s62, s62, 3
	s_add_i32 s89, s89, s62
	s_add_i32 s89, s89, 0x2aab
.Lcv0_B_loop:
	s_cmp_ge_u32 s89, 0x5556
	s_cbranch_scc1 .Lcv0_B_done
	s_lshl_b32 s61, s89, 1
	s_load_dwordx4 s[64:67], s[94:95], 0x50
	s_load_dwordx2 s[68:69], s[94:95], 0x130
	v_and_b32_e32 v102, 63, v0
	v_lshlrev_b32_e32 v103, 6, v102
	v_add_u32_e32 v104, 0x1000, v103
	v_lshrrev_b32_e32 v105, 3, v102
	v_and_b32_e32 v106, 7, v102
	v_lshlrev_b32_e32 v105, 21, v105
	v_lshl_or_b32 v105, v106, 4, v105
	v_add_u32_e32 v106, 0x1000000, v105
	v_mov_b32_e32 v204, 1.0
	v_mov_b32_e32 v206, 0
	s_add_i32 s70, s61, 1
	s_cmp_lt_u32 s70, 0xaaab
	s_cselect_b32 s88, 1, 0
	s_waitcnt lgkmcnt(0)
	s_lshr_b32 s71, s61, 14
	s_and_b32 s72, s61, 0x3fff
	s_lshr_b32 s73, s71, 1
	s_and_b32 s74, s71, 1
	s_cmp_eq_u32 s74, 0
	s_cselect_b32 s76, s64, s66
	s_cselect_b32 s77, s65, s67
	s_lshl_b32 s75, s73, 14
	s_add_i32 s75, s75, s72
	s_lshl_b32 s75, s75, 13
	s_add_u32 s76, s76, s75
	s_addc_u32 s77, s77, 0
	global_load_dwordx4 v[38:41], v103, s[76:77]
	global_load_dwordx4 v[42:45], v103, s[76:77] offset:16
	global_load_dwordx4 v[46:49], v103, s[76:77] offset:32
	global_load_dwordx4 v[50:53], v103, s[76:77] offset:48
	global_load_dwordx4 v[54:57], v104, s[76:77]
	global_load_dwordx4 v[58:61], v104, s[76:77] offset:16
	global_load_dwordx4 v[62:65], v104, s[76:77] offset:32
	global_load_dwordx4 v[66:69], v104, s[76:77] offset:48
	s_cmp_eq_u32 s88, 0
	s_cbranch_scc1 .Lrw_cv_l1_B
	s_lshr_b32 s71, s70, 14
	s_and_b32 s72, s70, 0x3fff
	s_lshr_b32 s73, s71, 1
	s_and_b32 s74, s71, 1
	s_cmp_eq_u32 s74, 0
	s_cselect_b32 s78, s64, s66
	s_cselect_b32 s79, s65, s67
	s_lshl_b32 s75, s73, 14
	s_add_i32 s75, s75, s72
	s_lshl_b32 s75, s75, 13
	s_add_u32 s78, s78, s75
	s_addc_u32 s79, s79, 0
	global_load_dwordx4 v[70:73], v103, s[78:79]
	global_load_dwordx4 v[74:77], v103, s[78:79] offset:16
	global_load_dwordx4 v[78:81], v103, s[78:79] offset:32
	global_load_dwordx4 v[82:85], v103, s[78:79] offset:48
	global_load_dwordx4 v[86:89], v104, s[78:79]
	global_load_dwordx4 v[90:93], v104, s[78:79] offset:16
	global_load_dwordx4 v[94:97], v104, s[78:79] offset:32
	global_load_dwordx4 v[98:101], v104, s[78:79] offset:48

; __device__ __forceinline__ void peer_convert_rows(KP P, const Ctx& c, int g_lo, int g_hi, int rank, int nranks) {
;     ...
;     for (int g0 = g_lo + (rank * 8 + c.wave) * 2; g0 < g_hi; g0 += nranks * 16) {
.Lcv0_B_next:
	s_add_i32 s89, s89, 0x700
	s_branch .Lcv0_B_loop

; __device__ __forceinline__ KP kp_fresh() { KP p = (KP)__builtin_amdgcn_kernarg_segment_ptr(); asm volatile("" : "+s"(p)); return p; }
; template <int LAYER, bool LAST> __device__ __forceinline__ void peer_phases(LAS unsigned char* lds, const XcdBarrier& bar) {
;     ...
;         if (!LAST && _rep == 0) { constexpr int NR = 8 * 16384, SH = (NR + 2) / 3; const int lo = LAYER * SH, hi = (LAYER == 2) ? NR : (LAYER + 1) * SH;
;             if ((int)gridDim.x == 256) { if ((int)blockIdx.x >= 32) peer_convert_rows(kp_fresh(), make_ctx(lds), lo, hi, (int)blockIdx.x - 32, 224); }
;             else peer_convert_rows(kp_fresh(), make_ctx(lds), lo, hi, (int)blockIdx.x, (int)gridDim.x); }
.LBB0_1044:
	v_cndmask_b32_e64 v2, 0, 1, s[40:41]
	s_andn2_b64 vcc, exec, s[0:1]
	v_cmp_ne_u32_e64 s[0:1], 1, v2
	s_nop 1
	v_writelane_b32 v239, s0, 25
	s_nop 1
	v_writelane_b32 v239, s1, 26
	s_cbranch_vccnz .LBB0_1061
	v_readlane_b32 s0, v239, 25
	v_readlane_b32 s1, v239, 26
	s_and_b64 vcc, exec, s[0:1]
	s_cbranch_vccnz .LBB0_1061
	s_branch .LBB0_1061
